# conv item: the 32 in-window rows' GLU inputs also fetched as one batch of 64 loads at section start (compiler kept only 1-2 in flight)
# speedup vs baseline: 1.0140x; 1.0140x over previous
; __device__ __forceinline__ float bf2f(unsigned short b) { return __uint_as_float((unsigned)b << 16); }
; __device__ __forceinline__ float sigmoidf_(float x) { return frcp(1.0f + fexp2(-1.4426950408889634f * x)); }
; __device__ __forceinline__ void conv_item(LAS unsigned char* lds, const bf16* PROJ, bf16* MIX, const float* cw, const float* cb, const float* lg, const float* lb, int item, int tid) {
;     ...
;     for (int i = 0; i < 62; ++i) { float hv = 0.f;
;         if (pos0 - 30 + i >= 0) { const bf16* rp = PROJ + (size_t)(row0 - 30 + i) * NPROJ; const float a = bf2f(rp[1536 + c]), g = bf2f(rp[2048 + c]); hv = a * sigmoidf_(g); }
;         hw[i] = hv; }
.LBB0_432:
	s_mov_b64 s[100:101], 0x1400
	v_add_co_u32_e32 v36, vcc, 0xc00, v2
	s_nop 1
	v_addc_co_u32_e32 v37, vcc, 0, v3, vcc
	global_load_ushort v160, v[36:37], off
	global_load_ushort v161, v[36:37], off offset:1024
	v_lshl_add_u64 v[36:37], v[36:37], 0, s[100:101]
	global_load_ushort v162, v[36:37], off
	global_load_ushort v163, v[36:37], off offset:1024
	v_lshl_add_u64 v[36:37], v[36:37], 0, s[100:101]
	global_load_ushort v164, v[36:37], off
	global_load_ushort v165, v[36:37], off offset:1024
	v_lshl_add_u64 v[36:37], v[36:37], 0, s[100:101]
	global_load_ushort v166, v[36:37], off
	global_load_ushort v167, v[36:37], off offset:1024
	v_lshl_add_u64 v[36:37], v[36:37], 0, s[100:101]
	global_load_ushort v168, v[36:37], off
	global_load_ushort v169, v[36:37], off offset:1024
	v_lshl_add_u64 v[36:37], v[36:37], 0, s[100:101]
	global_load_ushort v170, v[36:37], off
	global_load_ushort v171, v[36:37], off offset:1024
	v_lshl_add_u64 v[36:37], v[36:37], 0, s[100:101]
	global_load_ushort v172, v[36:37], off
	global_load_ushort v173, v[36:37], off offset:1024
	v_lshl_add_u64 v[36:37], v[36:37], 0, s[100:101]
	global_load_ushort v174, v[36:37], off
	global_load_ushort v175, v[36:37], off offset:1024
	v_lshl_add_u64 v[36:37], v[36:37], 0, s[100:101]
	global_load_ushort v176, v[36:37], off
	global_load_ushort v177, v[36:37], off offset:1024
	v_lshl_add_u64 v[36:37], v[36:37], 0, s[100:101]
	global_load_ushort v178, v[36:37], off
	global_load_ushort v179, v[36:37], off offset:1024
	v_lshl_add_u64 v[36:37], v[36:37], 0, s[100:101]
	global_load_ushort v180, v[36:37], off
	global_load_ushort v181, v[36:37], off offset:1024
	v_lshl_add_u64 v[36:37], v[36:37], 0, s[100:101]
	global_load_ushort v182, v[36:37], off
	global_load_ushort v183, v[36:37], off offset:1024
	v_lshl_add_u64 v[36:37], v[36:37], 0, s[100:101]
	global_load_ushort v184, v[36:37], off
	global_load_ushort v185, v[36:37], off offset:1024
	v_lshl_add_u64 v[36:37], v[36:37], 0, s[100:101]
	global_load_ushort v186, v[36:37], off
	global_load_ushort v187, v[36:37], off offset:1024
	v_lshl_add_u64 v[36:37], v[36:37], 0, s[100:101]
	global_load_ushort v188, v[36:37], off
	global_load_ushort v189, v[36:37], off offset:1024
	v_lshl_add_u64 v[36:37], v[36:37], 0, s[100:101]
	global_load_ushort v190, v[36:37], off
	global_load_ushort v191, v[36:37], off offset:1024
	v_lshl_add_u64 v[36:37], v[36:37], 0, s[100:101]
	global_load_ushort v192, v[36:37], off
	global_load_ushort v193, v[36:37], off offset:1024
	v_lshl_add_u64 v[36:37], v[36:37], 0, s[100:101]
	global_load_ushort v194, v[36:37], off
	global_load_ushort v195, v[36:37], off offset:1024
	v_lshl_add_u64 v[36:37], v[36:37], 0, s[100:101]
	global_load_ushort v196, v[36:37], off
	global_load_ushort v197, v[36:37], off offset:1024
	v_lshl_add_u64 v[36:37], v[36:37], 0, s[100:101]
	global_load_ushort v198, v[36:37], off
	global_load_ushort v199, v[36:37], off offset:1024
	v_lshl_add_u64 v[36:37], v[36:37], 0, s[100:101]
	global_load_ushort v202, v[36:37], off
	global_load_ushort v203, v[36:37], off offset:1024
	v_lshl_add_u64 v[36:37], v[36:37], 0, s[100:101]
	global_load_ushort v204, v[36:37], off
	global_load_ushort v205, v[36:37], off offset:1024
	v_lshl_add_u64 v[36:37], v[36:37], 0, s[100:101]
	global_load_ushort v206, v[36:37], off
	global_load_ushort v207, v[36:37], off offset:1024
	v_lshl_add_u64 v[36:37], v[36:37], 0, s[100:101]
	global_load_ushort v208, v[36:37], off
	global_load_ushort v209, v[36:37], off offset:1024
	v_lshl_add_u64 v[36:37], v[36:37], 0, s[100:101]
	global_load_ushort v210, v[36:37], off
	global_load_ushort v211, v[36:37], off offset:1024
	v_lshl_add_u64 v[36:37], v[36:37], 0, s[100:101]
	global_load_ushort v212, v[36:37], off
	global_load_ushort v213, v[36:37], off offset:1024
	v_lshl_add_u64 v[36:37], v[36:37], 0, s[100:101]
	global_load_ushort v214, v[36:37], off
	global_load_ushort v215, v[36:37], off offset:1024
	v_lshl_add_u64 v[36:37], v[36:37], 0, s[100:101]
	global_load_ushort v216, v[36:37], off
	global_load_ushort v217, v[36:37], off offset:1024
	v_lshl_add_u64 v[36:37], v[36:37], 0, s[100:101]
	global_load_ushort v218, v[36:37], off
	global_load_ushort v219, v[36:37], off offset:1024
	v_lshl_add_u64 v[36:37], v[36:37], 0, s[100:101]
	global_load_ushort v220, v[36:37], off
	global_load_ushort v221, v[36:37], off offset:1024
	v_lshl_add_u64 v[36:37], v[36:37], 0, s[100:101]
	global_load_ushort v222, v[36:37], off
	global_load_ushort v223, v[36:37], off offset:1024
	v_lshl_add_u64 v[36:37], v[36:37], 0, s[100:101]
	global_load_ushort v224, v[36:37], off
	global_load_ushort v225, v[36:37], off offset:1024
	s_waitcnt vmcnt(0)
	v_add_co_u32_e32 v36, vcc, 0x1000, v2
	v_mov_b32_e32 v34, v160
	s_nop 0
	v_addc_co_u32_e32 v37, vcc, 0, v3, vcc
	v_mov_b32_e32 v36, v161
	v_add_co_u32_e32 v56, vcc, 0x2000, v2
	s_movk_i32 s3, 0x4000
	s_nop 0
	v_addc_co_u32_e32 v57, vcc, 0, v3, vcc
	v_readlane_b32 s0, v255, 20
	v_readlane_b32 s1, v255, 21
	s_lshl_b64 s[14:15], s[0:1], 2
	s_add_u32 s0, s18, s14
	s_addc_u32 s1, s19, s15
	v_and_b32_e32 v35, 63, v200
	v_cmp_eq_u32_e64 s[8:9], 0, v35
	s_waitcnt vmcnt(1)
	v_lshlrev_b32_e32 v34, 16, v34
	s_waitcnt vmcnt(0)
	v_lshlrev_b32_e32 v36, 16, v36
	v_mul_f32_e32 v36, 0xbfb8aa3b, v36
	v_exp_f32_e32 v36, v36
	s_nop 0
	v_add_f32_e32 v36, 1.0, v36
	v_rcp_f32_e32 v36, v36
	s_nop 0
	v_mul_f32_e32 v37, v36, v34
	v_mov_b32_e32 v36, v163
	v_mov_b32_e32 v34, v162
	v_add_co_u32_e32 v56, vcc, 0x3000, v2
	s_waitcnt vmcnt(1)
	v_lshlrev_b32_e32 v36, 16, v36
	v_addc_co_u32_e32 v57, vcc, 0, v3, vcc
	v_mul_f32_e32 v36, 0xbfb8aa3b, v36
	v_mov_b32_e32 v39, v165
	v_exp_f32_e32 v36, v36
	s_waitcnt vmcnt(1)
; __device__ __forceinline__ float bf2f(unsigned short b) { return __uint_as_float((unsigned)b << 16); }
; __device__ __forceinline__ float sigmoidf_(float x) { return frcp(1.0f + fexp2(-1.4426950408889634f * x)); }
; __device__ __forceinline__ void conv_item(LAS unsigned char* lds, const bf16* PROJ, bf16* MIX, const float* cw, const float* cb, const float* lg, const float* lb, int item, int tid) {
;     ...
;     for (int i = 0; i < 62; ++i) { float hv = 0.f;
;         if (pos0 - 30 + i >= 0) { const bf16* rp = PROJ + (size_t)(row0 - 30 + i) * NPROJ; const float a = bf2f(rp[1536 + c]), g = bf2f(rp[2048 + c]); hv = a * sigmoidf_(g); }
;         hw[i] = hv; }
	v_lshlrev_b32_e32 v34, 16, v34
	v_add_f32_e32 v36, 1.0, v36
	v_rcp_f32_e32 v36, v36
	s_waitcnt vmcnt(0)
	v_lshlrev_b32_e32 v39, 16, v39
	v_mul_f32_e32 v36, v36, v34
	v_mov_b32_e32 v34, v164
	v_add_co_u32_e32 v56, vcc, s3, v2
	v_mul_f32_e32 v39, 0xbfb8aa3b, v39
	s_nop 0
	v_addc_co_u32_e32 v57, vcc, 0, v3, vcc
	v_mov_b32_e32 v42, v167
	v_exp_f32_e32 v39, v39
	s_movk_i32 s3, 0x7000
	v_add_f32_e32 v39, 1.0, v39
	v_rcp_f32_e32 v39, v39
	s_waitcnt vmcnt(1)
	v_lshlrev_b32_e32 v34, 16, v34
	v_mul_f32_e32 v39, v39, v34
	v_mov_b32_e32 v34, v166
	v_add_co_u32_e32 v56, vcc, s35, v2
	s_waitcnt vmcnt(1)
	v_lshlrev_b32_e32 v42, 16, v42
	v_mul_f32_e32 v42, 0xbfb8aa3b, v42
	v_exp_f32_e32 v42, v42
	v_addc_co_u32_e32 v57, vcc, 0, v3, vcc
	v_add_f32_e32 v42, 1.0, v42
	v_rcp_f32_e32 v42, v42
	s_waitcnt vmcnt(0)
	v_lshlrev_b32_e32 v34, 16, v34
	v_mul_f32_e32 v42, v42, v34
	v_mov_b32_e32 v34, v168
	v_add_co_u32_e32 v56, vcc, s3, v2
	s_mov_b32 s3, 0x9000
	s_nop 0
	v_addc_co_u32_e32 v57, vcc, 0, v3, vcc
	v_mov_b32_e32 v47, v169
	v_mov_b32_e32 v48, v171
	s_waitcnt vmcnt(2)
	v_lshlrev_b32_e32 v34, 16, v34
	s_waitcnt vmcnt(1)
	v_lshlrev_b32_e32 v47, 16, v47
	v_mul_f32_e32 v47, 0xbfb8aa3b, v47
	v_exp_f32_e32 v47, v47
	s_waitcnt vmcnt(0)
	v_lshlrev_b32_e32 v48, 16, v48
	v_mul_f32_e32 v48, 0xbfb8aa3b, v48
	v_exp_f32_e32 v48, v48
	v_add_f32_e32 v47, 1.0, v47
	v_rcp_f32_e32 v47, v47
	v_add_f32_e32 v48, 1.0, v48
	v_rcp_f32_e32 v48, v48
	v_mul_f32_e32 v47, v47, v34
	v_mov_b32_e32 v34, v170
	v_add_co_u32_e32 v56, vcc, s37, v2
	s_waitcnt vmcnt(0)
	v_lshlrev_b32_e32 v34, 16, v34
	v_addc_co_u32_e32 v57, vcc, 0, v3, vcc
	v_mov_b32_e32 v53, v173
	v_mul_f32_e32 v48, v48, v34
	v_mov_b32_e32 v34, v172
	v_add_co_u32_e32 v56, vcc, s3, v2
	s_mov_b32 s3, 0xd000
	s_nop 0
	v_addc_co_u32_e32 v57, vcc, 0, v3, vcc
	v_add_co_u32_e32 v58, vcc, s38, v2
	s_waitcnt vmcnt(1)
	v_lshlrev_b32_e32 v53, 16, v53
	v_mul_f32_e32 v53, 0xbfb8aa3b, v53
	v_exp_f32_e32 v53, v53
	s_waitcnt vmcnt(0)
	v_lshlrev_b32_e32 v34, 16, v34
	v_addc_co_u32_e32 v59, vcc, 0, v3, vcc
	v_add_f32_e32 v53, 1.0, v53
	v_rcp_f32_e32 v53, v53
	s_nop 0
	v_mul_f32_e32 v53, v53, v34
	v_mov_b32_e32 v34, v174
	s_waitcnt vmcnt(0)
	v_lshlrev_b32_e32 v34, 16, v34
	v_mov_b32_e32 v56, v175
	s_waitcnt vmcnt(0)
	v_lshlrev_b32_e32 v56, 16, v56
	v_mul_f32_e32 v56, 0xbfb8aa3b, v56
	v_exp_f32_e32 v56, v56
	s_nop 0
	v_add_f32_e32 v56, 1.0, v56
	v_rcp_f32_e32 v56, v56
	s_nop 0
	v_mul_f32_e32 v56, v56, v34
	v_mov_b32_e32 v34, v176
	v_add_co_u32_e32 v58, vcc, s39, v2
	s_waitcnt vmcnt(0)
	v_lshlrev_b32_e32 v34, 16, v34
	v_addc_co_u32_e32 v59, vcc, 0, v3, vcc
	v_mov_b32_e32 v57, v177
	v_add_co_u32_e32 v60, vcc, s3, v2
	s_mov_b32 s3, 0x11000
	s_nop 0
	v_addc_co_u32_e32 v61, vcc, 0, v3, vcc
	s_waitcnt vmcnt(0)
	v_lshlrev_b32_e32 v57, 16, v57
	v_mul_f32_e32 v57, 0xbfb8aa3b, v57
	v_exp_f32_e32 v57, v57
	s_nop 0
	v_add_f32_e32 v57, 1.0, v57
	v_rcp_f32_e32 v57, v57
	s_nop 0
	v_mul_f32_e32 v57, v57, v34
	v_mov_b32_e32 v34, v178
	s_waitcnt vmcnt(0)
	v_lshlrev_b32_e32 v34, 16, v34
	v_mov_b32_e32 v58, v179
	s_waitcnt vmcnt(0)
	v_lshlrev_b32_e32 v58, 16, v58
	v_mul_f32_e32 v58, 0xbfb8aa3b, v58
	v_mov_b32_e32 v59, v181
	v_exp_f32_e32 v58, v58
	s_waitcnt vmcnt(0)
	v_lshlrev_b32_e32 v59, 16, v59
	v_add_f32_e32 v58, 1.0, v58
	v_rcp_f32_e32 v58, v58
	v_mul_f32_e32 v59, 0xbfb8aa3b, v59
	v_exp_f32_e32 v59, v59
	v_mul_f32_e32 v58, v58, v34
	v_mov_b32_e32 v34, v180
	v_add_f32_e32 v59, 1.0, v59
	v_rcp_f32_e32 v59, v59
	v_add_co_u32_e32 v60, vcc, s42, v2
	s_waitcnt vmcnt(0)
	v_lshlrev_b32_e32 v34, 16, v34
	v_addc_co_u32_e32 v61, vcc, 0, v3, vcc
	v_mul_f32_e32 v59, v59, v34
	v_mov_b32_e32 v34, v182
	v_add_co_u32_e32 v66, vcc, s44, v2
	v_mov_b32_e32 v60, v183
	s_nop 0
	v_addc_co_u32_e32 v67, vcc, 0, v3, vcc
	s_waitcnt vmcnt(1)
	v_lshlrev_b32_e32 v34, 16, v34
	s_waitcnt vmcnt(0)
	v_lshlrev_b32_e32 v60, 16, v60
	v_mul_f32_e32 v60, 0xbfb8aa3b, v60
	v_exp_f32_e32 v60, v60
	s_nop 0
	v_add_f32_e32 v60, 1.0, v60
	v_rcp_f32_e32 v60, v60
	s_nop 0
	v_mul_f32_e32 v60, v60, v34
	v_mov_b32_e32 v34, v184
	v_add_co_u32_e32 v66, vcc, s3, v2
	s_mov_b32 s3, 0x12000
	s_nop 0
	v_addc_co_u32_e32 v67, vcc, 0, v3, vcc
	v_mov_b32_e32 v61, v185
	v_mov_b32_e32 v63, v187
	s_waitcnt vmcnt(2)
	v_lshlrev_b32_e32 v34, 16, v34
	s_waitcnt vmcnt(1)
	v_lshlrev_b32_e32 v61, 16, v61
	v_mul_f32_e32 v61, 0xbfb8aa3b, v61
	v_exp_f32_e32 v61, v61
	s_waitcnt vmcnt(0)
	v_lshlrev_b32_e32 v63, 16, v63
	v_mul_f32_e32 v63, 0xbfb8aa3b, v63
	v_exp_f32_e32 v63, v63
	v_add_f32_e32 v61, 1.0, v61
	v_rcp_f32_e32 v61, v61
	v_add_f32_e32 v63, 1.0, v63
	v_rcp_f32_e32 v63, v63
	v_mul_f32_e32 v61, v61, v34
	v_mov_b32_e32 v34, v186
	v_add_co_u32_e32 v66, vcc, s3, v2
	s_mov_b32 s3, 0x13000
	s_nop 0
	v_addc_co_u32_e32 v67, vcc, 0, v3, vcc
	v_mov_b32_e32 v65, v189
	s_waitcnt vmcnt(1)
	v_lshlrev_b32_e32 v34, 16, v34
	v_mul_f32_e32 v63, v63, v34
	v_mov_b32_e32 v34, v188
	v_add_co_u32_e32 v66, vcc, s3, v2
	s_mov_b32 s3, 0x14000
	s_waitcnt vmcnt(1)
	v_lshlrev_b32_e32 v65, 16, v65
	v_mul_f32_e32 v65, 0xbfb8aa3b, v65
	v_exp_f32_e32 v65, v65
	v_addc_co_u32_e32 v67, vcc, 0, v3, vcc
	v_add_co_u32_e32 v72, vcc, s3, v2
	v_add_f32_e32 v65, 1.0, v65
	v_rcp_f32_e32 v65, v65
	v_addc_co_u32_e32 v73, vcc, 0, v3, vcc
	s_mov_b32 s3, 0x17000
	s_waitcnt vmcnt(0)
	v_lshlrev_b32_e32 v34, 16, v34
	v_mul_f32_e32 v65, v65, v34
	v_mov_b32_e32 v34, v190
	s_waitcnt vmcnt(0)
	v_lshlrev_b32_e32 v34, 16, v34
	v_mov_b32_e32 v66, v191
	s_waitcnt vmcnt(0)
	v_lshlrev_b32_e32 v66, 16, v66
	v_mul_f32_e32 v66, 0xbfb8aa3b, v66
	v_exp_f32_e32 v66, v66
	s_nop 0
	v_add_f32_e32 v66, 1.0, v66
	v_rcp_f32_e32 v66, v66
	s_nop 0
	v_mul_f32_e32 v66, v66, v34
	v_mov_b32_e32 v34, v192
	v_add_co_u32_e32 v72, vcc, s36, v2
	s_waitcnt vmcnt(0)
; __device__ __forceinline__ float bf2f(unsigned short b) { return __uint_as_float((unsigned)b << 16); }
; __device__ __forceinline__ float sigmoidf_(float x) { return frcp(1.0f + fexp2(-1.4426950408889634f * x)); }
; __device__ __forceinline__ void conv_item(LAS unsigned char* lds, const bf16* PROJ, bf16* MIX, const float* cw, const float* cb, const float* lg, const float* lb, int item, int tid) {
;     ...
;     for (int i = 0; i < 62; ++i) { float hv = 0.f;
;         if (pos0 - 30 + i >= 0) { const bf16* rp = PROJ + (size_t)(row0 - 30 + i) * NPROJ; const float a = bf2f(rp[1536 + c]), g = bf2f(rp[2048 + c]); hv = a * sigmoidf_(g); }
;         hw[i] = hv; }
	v_lshlrev_b32_e32 v34, 16, v34
	v_addc_co_u32_e32 v73, vcc, 0, v3, vcc
	v_mov_b32_e32 v67, v193
	v_mov_b32_e32 v68, v195
	s_waitcnt vmcnt(1)
	v_lshlrev_b32_e32 v67, 16, v67
	v_mul_f32_e32 v67, 0xbfb8aa3b, v67
	v_exp_f32_e32 v67, v67
	s_waitcnt vmcnt(0)
	v_lshlrev_b32_e32 v68, 16, v68
	v_mul_f32_e32 v68, 0xbfb8aa3b, v68
	v_exp_f32_e32 v68, v68
	v_add_f32_e32 v67, 1.0, v67
	v_rcp_f32_e32 v67, v67
	v_add_f32_e32 v68, 1.0, v68
	v_rcp_f32_e32 v68, v68
	v_mul_f32_e32 v67, v67, v34
	v_mov_b32_e32 v34, v194
	v_add_co_u32_e32 v72, vcc, s3, v2
	s_mov_b32 s3, 0x18000
	s_nop 0
	v_addc_co_u32_e32 v73, vcc, 0, v3, vcc
	v_mov_b32_e32 v71, v197
	s_waitcnt vmcnt(1)
	v_lshlrev_b32_e32 v34, 16, v34
	v_mul_f32_e32 v68, v68, v34
	v_mov_b32_e32 v34, v196
	v_add_co_u32_e32 v72, vcc, s3, v2
	s_mov_b32 s3, 0x19000
	s_waitcnt vmcnt(1)
	v_lshlrev_b32_e32 v71, 16, v71
	v_mul_f32_e32 v71, 0xbfb8aa3b, v71
	v_exp_f32_e32 v71, v71
	v_addc_co_u32_e32 v73, vcc, 0, v3, vcc
	v_add_co_u32_e32 v74, vcc, s3, v2
	v_add_f32_e32 v71, 1.0, v71
	v_rcp_f32_e32 v71, v71
	v_addc_co_u32_e32 v75, vcc, 0, v3, vcc
	s_mov_b32 s3, 0x1c000
	s_waitcnt vmcnt(0)
	v_lshlrev_b32_e32 v34, 16, v34
	v_mul_f32_e32 v71, v71, v34
	v_mov_b32_e32 v34, v198
	s_waitcnt vmcnt(0)
	v_lshlrev_b32_e32 v34, 16, v34
	v_mov_b32_e32 v72, v199
	s_waitcnt vmcnt(0)
	v_lshlrev_b32_e32 v72, 16, v72
	v_mul_f32_e32 v72, 0xbfb8aa3b, v72
	v_exp_f32_e32 v72, v72
	s_nop 0
	v_add_f32_e32 v72, 1.0, v72
	v_rcp_f32_e32 v72, v72
	s_nop 0
	v_mul_f32_e32 v72, v72, v34
	v_mov_b32_e32 v34, v202
	v_add_co_u32_e32 v74, vcc, s52, v2
	s_waitcnt vmcnt(0)
	v_lshlrev_b32_e32 v34, 16, v34
	v_addc_co_u32_e32 v75, vcc, 0, v3, vcc
	v_mov_b32_e32 v73, v203
	v_add_co_u32_e32 v88, vcc, s3, v2
	s_mov_b32 s3, 0x1d000
	s_nop 0
	v_addc_co_u32_e32 v89, vcc, 0, v3, vcc
	s_waitcnt vmcnt(0)
	v_lshlrev_b32_e32 v73, 16, v73
	v_mul_f32_e32 v73, 0xbfb8aa3b, v73
	v_exp_f32_e32 v73, v73
	s_nop 0
	v_add_f32_e32 v73, 1.0, v73
	v_rcp_f32_e32 v73, v73
	s_nop 0
	v_mul_f32_e32 v73, v73, v34
	v_mov_b32_e32 v34, v204
	s_waitcnt vmcnt(0)
	v_lshlrev_b32_e32 v34, 16, v34
	v_mov_b32_e32 v74, v205
	s_waitcnt vmcnt(0)
	v_lshlrev_b32_e32 v74, 16, v74
	v_mul_f32_e32 v74, 0xbfb8aa3b, v74
	v_mov_b32_e32 v75, v207
	v_exp_f32_e32 v74, v74
	s_waitcnt vmcnt(0)
	v_lshlrev_b32_e32 v75, 16, v75
	v_add_f32_e32 v74, 1.0, v74
	v_rcp_f32_e32 v74, v74
	v_mul_f32_e32 v75, 0xbfb8aa3b, v75
	v_exp_f32_e32 v75, v75
	v_mul_f32_e32 v74, v74, v34
	v_mov_b32_e32 v34, v206
	v_add_co_u32_e32 v88, vcc, s3, v2
	v_add_f32_e32 v75, 1.0, v75
	s_nop 0
	v_addc_co_u32_e32 v89, vcc, 0, v3, vcc
	v_mov_b32_e32 v76, v209
	v_rcp_f32_e32 v75, v75
	s_mov_b32 s3, 0x1e000
	s_waitcnt vmcnt(1)
	v_lshlrev_b32_e32 v34, 16, v34
	v_mul_f32_e32 v75, v75, v34
	v_mov_b32_e32 v34, v208
	v_add_co_u32_e32 v88, vcc, s3, v2
	s_mov_b32 s3, 0x20000
	s_waitcnt vmcnt(1)
	v_lshlrev_b32_e32 v76, 16, v76
	v_mul_f32_e32 v76, 0xbfb8aa3b, v76
	v_exp_f32_e32 v76, v76
	v_addc_co_u32_e32 v89, vcc, 0, v3, vcc
	v_add_f32_e32 v76, 1.0, v76
	v_rcp_f32_e32 v76, v76
	s_waitcnt vmcnt(0)
	v_lshlrev_b32_e32 v34, 16, v34
	v_mul_f32_e32 v76, v76, v34
	v_mov_b32_e32 v34, v210
	v_add_co_u32_e32 v88, vcc, s3, v2
	s_mov_b32 s3, 0x22000
	s_nop 0
	v_addc_co_u32_e32 v89, vcc, 0, v3, vcc
	v_mov_b32_e32 v87, v211
	v_add_co_u32_e32 v94, vcc, s53, v2
	s_waitcnt vmcnt(1)
	v_lshlrev_b32_e32 v34, 16, v34
	v_addc_co_u32_e32 v95, vcc, 0, v3, vcc
	s_waitcnt vmcnt(0)
	v_lshlrev_b32_e32 v87, 16, v87
	v_mul_f32_e32 v87, 0xbfb8aa3b, v87
	v_exp_f32_e32 v87, v87
	s_nop 0
	v_add_f32_e32 v87, 1.0, v87
	v_rcp_f32_e32 v87, v87
	s_nop 0
	v_mul_f32_e32 v87, v87, v34
	v_mov_b32_e32 v34, v212
	s_waitcnt vmcnt(0)
	v_lshlrev_b32_e32 v34, 16, v34
	v_mov_b32_e32 v88, v213
	s_waitcnt vmcnt(0)
	v_lshlrev_b32_e32 v88, 16, v88
	v_mul_f32_e32 v88, 0xbfb8aa3b, v88
	v_mov_b32_e32 v89, v215
	v_exp_f32_e32 v88, v88
	s_waitcnt vmcnt(0)
	v_lshlrev_b32_e32 v89, 16, v89
	v_add_f32_e32 v88, 1.0, v88
	v_rcp_f32_e32 v88, v88
	v_mul_f32_e32 v89, 0xbfb8aa3b, v89
	v_exp_f32_e32 v89, v89
	v_mul_f32_e32 v88, v88, v34
	v_mov_b32_e32 v34, v214
	v_add_co_u32_e32 v94, vcc, s3, v2
	v_add_f32_e32 v89, 1.0, v89
	s_nop 0
	v_addc_co_u32_e32 v95, vcc, 0, v3, vcc
	v_mov_b32_e32 v92, v217
	v_rcp_f32_e32 v89, v89
	s_mov_b32 s3, 0x23000
	s_waitcnt vmcnt(1)
	v_lshlrev_b32_e32 v34, 16, v34
	v_mul_f32_e32 v89, v89, v34
	v_mov_b32_e32 v34, v216
	v_add_co_u32_e32 v94, vcc, s3, v2
	s_mov_b32 s3, 0x25000
	s_waitcnt vmcnt(1)
	v_lshlrev_b32_e32 v92, 16, v92
	v_mul_f32_e32 v92, 0xbfb8aa3b, v92
	v_exp_f32_e32 v92, v92
	v_addc_co_u32_e32 v95, vcc, 0, v3, vcc
	v_add_co_u32_e32 v96, vcc, s3, v2
	v_add_f32_e32 v92, 1.0, v92
	v_rcp_f32_e32 v92, v92
	v_addc_co_u32_e32 v97, vcc, 0, v3, vcc
	s_mov_b32 s3, 0x27000
	s_waitcnt vmcnt(0)
	v_lshlrev_b32_e32 v34, 16, v34
	v_mul_f32_e32 v92, v92, v34
	v_mov_b32_e32 v34, v218
	s_waitcnt vmcnt(0)
	v_lshlrev_b32_e32 v34, 16, v34
	v_mov_b32_e32 v94, v219
	v_mov_b32_e32 v95, v221
	s_waitcnt vmcnt(1)
	v_lshlrev_b32_e32 v94, 16, v94
	v_mul_f32_e32 v94, 0xbfb8aa3b, v94
	v_exp_f32_e32 v94, v94
	s_waitcnt vmcnt(0)
	v_lshlrev_b32_e32 v95, 16, v95
	v_mul_f32_e32 v95, 0xbfb8aa3b, v95
	v_exp_f32_e32 v95, v95
	v_add_f32_e32 v94, 1.0, v94
	v_rcp_f32_e32 v94, v94
	v_add_f32_e32 v95, 1.0, v95
	v_rcp_f32_e32 v95, v95
	v_mul_f32_e32 v94, v94, v34
	v_mov_b32_e32 v34, v220
	v_add_co_u32_e32 v96, vcc, s55, v2
	s_waitcnt vmcnt(0)
	v_lshlrev_b32_e32 v34, 16, v34
	v_addc_co_u32_e32 v97, vcc, 0, v3, vcc
	v_mul_f32_e32 v95, v95, v34
	v_mov_b32_e32 v34, v222
	v_add_co_u32_e32 v2, vcc, s3, v2
	v_mov_b32_e32 v96, v223
	s_nop 0
	v_addc_co_u32_e32 v3, vcc, 0, v3, vcc
	s_waitcnt vmcnt(1)
	v_lshlrev_b32_e32 v34, 16, v34
	s_waitcnt vmcnt(0)
; __device__ __forceinline__ void conv_item(LAS unsigned char* lds, const bf16* PROJ, bf16* MIX, const float* cw, const float* cb, const float* lg, const float* lb, int item, int tid) {
;     ...
;     float acc[32]; const float bias = cb[c];
; #pragma unroll
;     for (int tk = 0; tk < 32; ++tk) { float s = bias;
; #pragma unroll
;         for (int k = 0; k < 31; ++k) s += w[k] * hw[tk + k];
;         acc[tk] = s; }
	v_lshlrev_b32_e32 v96, 16, v96
	v_mul_f32_e32 v96, 0xbfb8aa3b, v96
	v_exp_f32_e32 v96, v96
	s_nop 0
	v_add_f32_e32 v96, 1.0, v96
	v_rcp_f32_e32 v96, v96
	s_nop 0
	v_mul_f32_e32 v96, v96, v34
	v_mov_b32_e32 v34, v225
	s_waitcnt vmcnt(0)
	v_lshlrev_b32_e32 v34, 16, v34
	v_mov_b32_e32 v2, v224
	v_mul_f32_e32 v34, 0xbfb8aa3b, v34
	v_exp_f32_e32 v34, v34
	s_waitcnt vmcnt(0)
	v_lshlrev_b32_e32 v2, 16, v2
	v_add_f32_e32 v34, 1.0, v34
	v_rcp_f32_e32 v34, v34
	s_nop 0
	v_mul_f32_e32 v97, v34, v2
	v_lshl_add_u64 v[2:3], v[200:201], 2, s[0:1]
	global_load_dword v34, v[2:3], off
	v_readfirstlane_b32 s0, v200
	s_ashr_i32 s3, s0, 4
	s_and_b32 s4, s3, -4
	s_waitcnt vmcnt(0)
	v_fma_f32 v93, v10, v93, v34
	v_fmac_f32_e32 v93, v9, v90
	v_fma_f32 v90, v10, v90, v34
	v_fmac_f32_e32 v93, v8, v91
	v_fmac_f32_e32 v90, v9, v91
	v_fma_f32 v2, v10, v91, v34
	v_fmac_f32_e32 v93, v7, v86
	v_fmac_f32_e32 v90, v8, v86
	v_fmac_f32_e32 v2, v9, v86
	v_fma_f32 v86, v10, v86, v34
	v_fmac_f32_e32 v93, v5, v85
	v_fmac_f32_e32 v90, v7, v85
	v_fmac_f32_e32 v2, v8, v85
	v_fmac_f32_e32 v86, v9, v85
	v_fma_f32 v3, v10, v85, v34
	v_fmac_f32_e32 v93, v0, v84
	v_fmac_f32_e32 v90, v5, v84
	v_fmac_f32_e32 v2, v7, v84
	v_fmac_f32_e32 v86, v8, v84
	v_fmac_f32_e32 v3, v9, v84
	v_fma_f32 v84, v10, v84, v34
	v_fmac_f32_e32 v93, v6, v83
	v_fmac_f32_e32 v90, v0, v83
	v_fmac_f32_e32 v2, v5, v83
	v_fmac_f32_e32 v86, v7, v83
	v_fmac_f32_e32 v3, v8, v83
	v_fmac_f32_e32 v84, v9, v83
	v_fma_f32 v83, v10, v83, v34
	v_fmac_f32_e32 v93, v4, v82
	v_fmac_f32_e32 v90, v6, v82
	v_fmac_f32_e32 v2, v0, v82
	v_fmac_f32_e32 v86, v5, v82
	v_fmac_f32_e32 v3, v7, v82
	v_fmac_f32_e32 v84, v8, v82
	v_fmac_f32_e32 v83, v9, v82
	v_fma_f32 v82, v10, v82, v34
	v_fmac_f32_e32 v93, v18, v81
	v_fmac_f32_e32 v90, v4, v81
	v_fmac_f32_e32 v2, v6, v81
	v_fmac_f32_e32 v86, v0, v81
	v_fmac_f32_e32 v3, v5, v81
	v_fmac_f32_e32 v84, v7, v81
	v_fmac_f32_e32 v83, v8, v81
	v_fmac_f32_e32 v82, v9, v81
	v_fma_f32 v81, v10, v81, v34
	v_fmac_f32_e32 v93, v17, v80
	v_fmac_f32_e32 v90, v18, v80
	v_fmac_f32_e32 v2, v4, v80
	v_fmac_f32_e32 v86, v6, v80
	v_fmac_f32_e32 v3, v0, v80
	v_fmac_f32_e32 v84, v5, v80
	v_fmac_f32_e32 v83, v7, v80
	v_fmac_f32_e32 v82, v8, v80
	v_fmac_f32_e32 v81, v9, v80
	v_fma_f32 v80, v10, v80, v34
	v_fmac_f32_e32 v93, v33, v79
	v_fmac_f32_e32 v90, v17, v79
	v_fmac_f32_e32 v2, v18, v79
	v_fmac_f32_e32 v86, v4, v79
	v_fmac_f32_e32 v3, v6, v79
	v_fmac_f32_e32 v84, v0, v79
	v_fmac_f32_e32 v83, v5, v79
	v_fmac_f32_e32 v82, v7, v79
	v_fmac_f32_e32 v81, v8, v79
	v_fmac_f32_e32 v80, v9, v79
	v_fma_f32 v79, v10, v79, v34
	v_fmac_f32_e32 v93, v16, v78
	v_fmac_f32_e32 v90, v33, v78
	v_fmac_f32_e32 v2, v17, v78
	v_fmac_f32_e32 v86, v18, v78
	v_fmac_f32_e32 v3, v4, v78
	v_fmac_f32_e32 v84, v6, v78
	v_fmac_f32_e32 v83, v0, v78
	v_fmac_f32_e32 v82, v5, v78
	v_fmac_f32_e32 v81, v7, v78
	v_fmac_f32_e32 v80, v8, v78
	v_fmac_f32_e32 v79, v9, v78
	v_fma_f32 v78, v10, v78, v34
	v_fmac_f32_e32 v93, v32, v77
	v_fmac_f32_e32 v90, v16, v77
	v_fmac_f32_e32 v2, v33, v77
	v_fmac_f32_e32 v86, v17, v77
	v_fmac_f32_e32 v3, v18, v77
	v_fmac_f32_e32 v84, v4, v77
	v_fmac_f32_e32 v83, v6, v77
	v_fmac_f32_e32 v82, v0, v77
	v_fmac_f32_e32 v81, v5, v77
	v_fmac_f32_e32 v80, v7, v77
	v_fmac_f32_e32 v79, v8, v77
	v_fmac_f32_e32 v78, v9, v77
	v_fma_f32 v77, v10, v77, v34
	v_fmac_f32_e32 v93, v31, v70
	v_fmac_f32_e32 v90, v32, v70
	v_fmac_f32_e32 v2, v16, v70
	v_fmac_f32_e32 v86, v33, v70
	v_fmac_f32_e32 v3, v17, v70
	v_fmac_f32_e32 v84, v18, v70
	v_fmac_f32_e32 v83, v4, v70
	v_fmac_f32_e32 v82, v6, v70
	v_fmac_f32_e32 v81, v0, v70
	v_fmac_f32_e32 v80, v5, v70
	v_fmac_f32_e32 v79, v7, v70
	v_fmac_f32_e32 v78, v8, v70
	v_fmac_f32_e32 v77, v9, v70
	v_fma_f32 v70, v10, v70, v34
	v_fmac_f32_e32 v93, v15, v69
	v_fmac_f32_e32 v90, v31, v69
	v_fmac_f32_e32 v2, v32, v69
	v_fmac_f32_e32 v86, v16, v69
	v_fmac_f32_e32 v3, v33, v69
	v_fmac_f32_e32 v84, v17, v69
	v_fmac_f32_e32 v83, v18, v69
	v_fmac_f32_e32 v82, v4, v69
	v_fmac_f32_e32 v81, v6, v69
	v_fmac_f32_e32 v80, v0, v69
	v_fmac_f32_e32 v79, v5, v69
	v_fmac_f32_e32 v78, v7, v69
	v_fmac_f32_e32 v77, v8, v69
	v_fmac_f32_e32 v70, v9, v69
	v_fma_f32 v69, v10, v69, v34
	v_fmac_f32_e32 v93, v14, v64
	v_fmac_f32_e32 v90, v15, v64
	v_fmac_f32_e32 v2, v31, v64
	v_fmac_f32_e32 v86, v32, v64
	v_fmac_f32_e32 v3, v16, v64
	v_fmac_f32_e32 v84, v33, v64
	v_fmac_f32_e32 v83, v17, v64
	v_fmac_f32_e32 v82, v18, v64
	v_fmac_f32_e32 v81, v4, v64
	v_fmac_f32_e32 v80, v6, v64
	v_fmac_f32_e32 v79, v0, v64
	v_fmac_f32_e32 v78, v5, v64
	v_fmac_f32_e32 v77, v7, v64
	v_fmac_f32_e32 v70, v8, v64
	v_fmac_f32_e32 v69, v9, v64
	v_fma_f32 v64, v10, v64, v34
	v_fmac_f32_e32 v93, v12, v62
	v_fmac_f32_e32 v90, v14, v62
	v_fmac_f32_e32 v2, v15, v62
	v_fmac_f32_e32 v86, v31, v62
	v_fmac_f32_e32 v3, v32, v62
	v_fmac_f32_e32 v84, v16, v62
	v_fmac_f32_e32 v83, v33, v62
	v_fmac_f32_e32 v82, v17, v62
	v_fmac_f32_e32 v81, v18, v62
	v_fmac_f32_e32 v80, v4, v62
	v_fmac_f32_e32 v79, v6, v62
	v_fmac_f32_e32 v78, v0, v62
	v_fmac_f32_e32 v77, v5, v62
	v_fmac_f32_e32 v70, v7, v62
	v_fmac_f32_e32 v69, v8, v62
	v_fmac_f32_e32 v64, v9, v62
	v_fma_f32 v62, v10, v62, v34
	v_fmac_f32_e32 v93, v11, v55
	v_fmac_f32_e32 v90, v12, v55
	v_fmac_f32_e32 v2, v14, v55
	v_fmac_f32_e32 v86, v15, v55
	v_fmac_f32_e32 v3, v31, v55
	v_fmac_f32_e32 v84, v32, v55
	v_fmac_f32_e32 v83, v16, v55
	v_fmac_f32_e32 v82, v33, v55
	v_fmac_f32_e32 v81, v17, v55
	v_fmac_f32_e32 v80, v18, v55
	v_fmac_f32_e32 v79, v4, v55
	v_fmac_f32_e32 v78, v6, v55
	v_fmac_f32_e32 v77, v0, v55
	v_fmac_f32_e32 v70, v5, v55
	v_fmac_f32_e32 v69, v7, v55
	v_fmac_f32_e32 v64, v8, v55
	v_fmac_f32_e32 v62, v9, v55
; __device__ __forceinline__ void conv_item(LAS unsigned char* lds, const bf16* PROJ, bf16* MIX, const float* cw, const float* cb, const float* lg, const float* lb, int item, int tid) {
;     ...
;     for (int tk = 0; tk < 32; ++tk) { float s = bias;
; #pragma unroll
;         for (int k = 0; k < 31; ++k) s += w[k] * hw[tk + k];
;         acc[tk] = s; }
	v_fma_f32 v55, v10, v55, v34
	v_fmac_f32_e32 v93, v13, v54
	v_fmac_f32_e32 v90, v11, v54
	v_fmac_f32_e32 v2, v12, v54
	v_fmac_f32_e32 v86, v14, v54
	v_fmac_f32_e32 v3, v15, v54
	v_fmac_f32_e32 v84, v31, v54
	v_fmac_f32_e32 v83, v32, v54
	v_fmac_f32_e32 v82, v16, v54
	v_fmac_f32_e32 v81, v33, v54
	v_fmac_f32_e32 v80, v17, v54
	v_fmac_f32_e32 v79, v18, v54
	v_fmac_f32_e32 v78, v4, v54
	v_fmac_f32_e32 v77, v6, v54
	v_fmac_f32_e32 v70, v0, v54
	v_fmac_f32_e32 v69, v5, v54
	v_fmac_f32_e32 v64, v7, v54
	v_fmac_f32_e32 v62, v8, v54
	v_fmac_f32_e32 v55, v9, v54
	v_fma_f32 v54, v10, v54, v34
	v_fmac_f32_e32 v93, v26, v52
	v_fmac_f32_e32 v90, v13, v52
	v_fmac_f32_e32 v2, v11, v52
	v_fmac_f32_e32 v86, v12, v52
	v_fmac_f32_e32 v3, v14, v52
	v_fmac_f32_e32 v84, v15, v52
	v_fmac_f32_e32 v83, v31, v52
	v_fmac_f32_e32 v82, v32, v52
	v_fmac_f32_e32 v81, v16, v52
	v_fmac_f32_e32 v80, v33, v52
	v_fmac_f32_e32 v79, v17, v52
	v_fmac_f32_e32 v78, v18, v52
	v_fmac_f32_e32 v77, v4, v52
	v_fmac_f32_e32 v70, v6, v52
	v_fmac_f32_e32 v69, v0, v52
	v_fmac_f32_e32 v64, v5, v52
	v_fmac_f32_e32 v62, v7, v52
	v_fmac_f32_e32 v55, v8, v52
	v_fmac_f32_e32 v54, v9, v52
	v_fma_f32 v52, v10, v52, v34
	v_fmac_f32_e32 v93, v30, v51
	v_fmac_f32_e32 v90, v26, v51
	v_fmac_f32_e32 v2, v13, v51
	v_fmac_f32_e32 v86, v11, v51
	v_fmac_f32_e32 v3, v12, v51
	v_fmac_f32_e32 v84, v14, v51
	v_fmac_f32_e32 v83, v15, v51
	v_fmac_f32_e32 v82, v31, v51
	v_fmac_f32_e32 v81, v32, v51
	v_fmac_f32_e32 v80, v16, v51
	v_fmac_f32_e32 v79, v33, v51
	v_fmac_f32_e32 v78, v17, v51
	v_fmac_f32_e32 v77, v18, v51
	v_fmac_f32_e32 v70, v4, v51
	v_fmac_f32_e32 v69, v6, v51
	v_fmac_f32_e32 v64, v0, v51
	v_fmac_f32_e32 v62, v5, v51
	v_fmac_f32_e32 v55, v7, v51
	v_fmac_f32_e32 v54, v8, v51
	v_fmac_f32_e32 v52, v9, v51
	v_fma_f32 v51, v10, v51, v34
	v_fmac_f32_e32 v93, v25, v50
	v_fmac_f32_e32 v90, v30, v50
	v_fmac_f32_e32 v2, v26, v50
	v_fmac_f32_e32 v86, v13, v50
	v_fmac_f32_e32 v3, v11, v50
	v_fmac_f32_e32 v84, v12, v50
	v_fmac_f32_e32 v83, v14, v50
	v_fmac_f32_e32 v82, v15, v50
	v_fmac_f32_e32 v81, v31, v50
	v_fmac_f32_e32 v80, v32, v50
	v_fmac_f32_e32 v79, v16, v50
	v_fmac_f32_e32 v78, v33, v50
	v_fmac_f32_e32 v77, v17, v50
	v_fmac_f32_e32 v70, v18, v50
	v_fmac_f32_e32 v69, v4, v50
	v_fmac_f32_e32 v64, v6, v50
	v_fmac_f32_e32 v62, v0, v50
	v_fmac_f32_e32 v55, v5, v50
	v_fmac_f32_e32 v54, v7, v50
	v_fmac_f32_e32 v52, v8, v50
	v_fmac_f32_e32 v51, v9, v50
	v_fma_f32 v50, v10, v50, v34
	v_fmac_f32_e32 v93, v29, v49
	v_fmac_f32_e32 v90, v25, v49
	v_fmac_f32_e32 v2, v30, v49
	v_fmac_f32_e32 v86, v26, v49
	v_fmac_f32_e32 v3, v13, v49
	v_fmac_f32_e32 v84, v11, v49
	v_fmac_f32_e32 v83, v12, v49
	v_fmac_f32_e32 v82, v14, v49
	v_fmac_f32_e32 v81, v15, v49
	v_fmac_f32_e32 v80, v31, v49
	v_fmac_f32_e32 v79, v32, v49
	v_fmac_f32_e32 v78, v16, v49
	v_fmac_f32_e32 v77, v33, v49
	v_fmac_f32_e32 v70, v17, v49
	v_fmac_f32_e32 v69, v18, v49
	v_fmac_f32_e32 v64, v4, v49
	v_fmac_f32_e32 v62, v6, v49
	v_fmac_f32_e32 v55, v0, v49
	v_fmac_f32_e32 v54, v5, v49
	v_fmac_f32_e32 v52, v7, v49
	v_fmac_f32_e32 v51, v8, v49
	v_fmac_f32_e32 v50, v9, v49
	v_fma_f32 v49, v10, v49, v34
	v_fmac_f32_e32 v93, v28, v46
	v_fmac_f32_e32 v90, v29, v46
	v_fmac_f32_e32 v2, v25, v46
	v_fmac_f32_e32 v86, v30, v46
	v_fmac_f32_e32 v3, v26, v46
	v_fmac_f32_e32 v84, v13, v46
	v_fmac_f32_e32 v83, v11, v46
	v_fmac_f32_e32 v82, v12, v46
	v_fmac_f32_e32 v81, v14, v46
	v_fmac_f32_e32 v80, v15, v46
	v_fmac_f32_e32 v79, v31, v46
	v_fmac_f32_e32 v78, v32, v46
	v_fmac_f32_e32 v77, v16, v46
	v_fmac_f32_e32 v70, v33, v46
	v_fmac_f32_e32 v69, v17, v46
	v_fmac_f32_e32 v64, v18, v46
	v_fmac_f32_e32 v62, v4, v46
	v_fmac_f32_e32 v55, v6, v46
	v_fmac_f32_e32 v54, v0, v46
	v_fmac_f32_e32 v52, v5, v46
	v_fmac_f32_e32 v51, v7, v46
	v_fmac_f32_e32 v50, v8, v46
	v_fmac_f32_e32 v49, v9, v46
	v_fma_f32 v46, v10, v46, v34
	v_fmac_f32_e32 v93, v24, v45
	v_fmac_f32_e32 v90, v28, v45
	v_fmac_f32_e32 v2, v29, v45
	v_fmac_f32_e32 v86, v25, v45
	v_fmac_f32_e32 v3, v30, v45
	v_fmac_f32_e32 v84, v26, v45
	v_fmac_f32_e32 v83, v13, v45
	v_fmac_f32_e32 v82, v11, v45
	v_fmac_f32_e32 v81, v12, v45
	v_fmac_f32_e32 v80, v14, v45
	v_fmac_f32_e32 v79, v15, v45
	v_fmac_f32_e32 v78, v31, v45
	v_fmac_f32_e32 v77, v32, v45
	v_fmac_f32_e32 v70, v16, v45
	v_fmac_f32_e32 v69, v33, v45
	v_fmac_f32_e32 v64, v17, v45
	v_fmac_f32_e32 v62, v18, v45
	v_fmac_f32_e32 v55, v4, v45
	v_fmac_f32_e32 v54, v6, v45
	v_fmac_f32_e32 v52, v0, v45
	v_fmac_f32_e32 v51, v5, v45
	v_fmac_f32_e32 v50, v7, v45
	v_fmac_f32_e32 v49, v8, v45
	v_fmac_f32_e32 v46, v9, v45
	v_fma_f32 v45, v10, v45, v34
	v_fmac_f32_e32 v93, v23, v44
	v_fmac_f32_e32 v90, v24, v44
	v_fmac_f32_e32 v2, v28, v44
	v_fmac_f32_e32 v86, v29, v44
	v_fmac_f32_e32 v3, v25, v44
	v_fmac_f32_e32 v84, v30, v44
	v_fmac_f32_e32 v83, v26, v44
	v_fmac_f32_e32 v82, v13, v44
	v_fmac_f32_e32 v81, v11, v44
	v_fmac_f32_e32 v80, v12, v44
	v_fmac_f32_e32 v79, v14, v44
	v_fmac_f32_e32 v78, v15, v44
	v_fmac_f32_e32 v77, v31, v44
	v_fmac_f32_e32 v70, v32, v44
	v_fmac_f32_e32 v69, v16, v44
	v_fmac_f32_e32 v64, v33, v44
	v_fmac_f32_e32 v62, v17, v44
	v_fmac_f32_e32 v55, v18, v44
	v_fmac_f32_e32 v54, v4, v44
	v_fmac_f32_e32 v52, v6, v44
	v_fmac_f32_e32 v51, v0, v44
	v_fmac_f32_e32 v50, v5, v44
	v_fmac_f32_e32 v49, v7, v44
	v_fmac_f32_e32 v46, v8, v44
	v_fmac_f32_e32 v45, v9, v44
	v_fma_f32 v44, v10, v44, v34
	v_fmac_f32_e32 v93, v21, v43
	v_fmac_f32_e32 v90, v23, v43
	v_fmac_f32_e32 v2, v24, v43
	v_fmac_f32_e32 v86, v28, v43
	v_fmac_f32_e32 v3, v29, v43
	v_fmac_f32_e32 v84, v25, v43
	v_fmac_f32_e32 v83, v30, v43
	v_fmac_f32_e32 v82, v26, v43
	v_fmac_f32_e32 v81, v13, v43
; __device__ __forceinline__ void conv_item(LAS unsigned char* lds, const bf16* PROJ, bf16* MIX, const float* cw, const float* cb, const float* lg, const float* lb, int item, int tid) {
;     ...
;     for (int tk = 0; tk < 32; ++tk) { float s = bias;
; #pragma unroll
;         for (int k = 0; k < 31; ++k) s += w[k] * hw[tk + k];
;         acc[tk] = s; }
	v_fmac_f32_e32 v80, v11, v43
	v_fmac_f32_e32 v79, v12, v43
	v_fmac_f32_e32 v78, v14, v43
	v_fmac_f32_e32 v77, v15, v43
	v_fmac_f32_e32 v70, v31, v43
	v_fmac_f32_e32 v69, v32, v43
	v_fmac_f32_e32 v64, v16, v43
	v_fmac_f32_e32 v62, v33, v43
	v_fmac_f32_e32 v55, v17, v43
	v_fmac_f32_e32 v54, v18, v43
	v_fmac_f32_e32 v52, v4, v43
	v_fmac_f32_e32 v51, v6, v43
	v_fmac_f32_e32 v50, v0, v43
	v_fmac_f32_e32 v49, v5, v43
	v_fmac_f32_e32 v46, v7, v43
	v_fmac_f32_e32 v45, v8, v43
	v_fmac_f32_e32 v44, v9, v43
	v_fma_f32 v43, v10, v43, v34
	v_fmac_f32_e32 v93, v19, v40
	v_fmac_f32_e32 v90, v21, v40
	v_fmac_f32_e32 v2, v23, v40
	v_fmac_f32_e32 v86, v24, v40
	v_fmac_f32_e32 v3, v28, v40
	v_fmac_f32_e32 v84, v29, v40
	v_fmac_f32_e32 v83, v25, v40
	v_fmac_f32_e32 v82, v30, v40
	v_fmac_f32_e32 v81, v26, v40
	v_fmac_f32_e32 v80, v13, v40
	v_fmac_f32_e32 v79, v11, v40
	v_fmac_f32_e32 v78, v12, v40
	v_fmac_f32_e32 v77, v14, v40
	v_fmac_f32_e32 v70, v15, v40
	v_fmac_f32_e32 v69, v31, v40
	v_fmac_f32_e32 v64, v32, v40
	v_fmac_f32_e32 v62, v16, v40
	v_fmac_f32_e32 v55, v33, v40
	v_fmac_f32_e32 v54, v17, v40
	v_fmac_f32_e32 v52, v18, v40
	v_fmac_f32_e32 v51, v4, v40
	v_fmac_f32_e32 v50, v6, v40
	v_fmac_f32_e32 v49, v0, v40
	v_fmac_f32_e32 v46, v5, v40
	v_fmac_f32_e32 v45, v7, v40
	v_fmac_f32_e32 v44, v8, v40
	v_fmac_f32_e32 v43, v9, v40
	v_fma_f32 v40, v10, v40, v34
	v_fmac_f32_e32 v93, v22, v41
	v_fmac_f32_e32 v90, v19, v41
	v_fmac_f32_e32 v2, v21, v41
	v_fmac_f32_e32 v86, v23, v41
	v_fmac_f32_e32 v3, v24, v41
	v_fmac_f32_e32 v84, v28, v41
	v_fmac_f32_e32 v83, v29, v41
	v_fmac_f32_e32 v82, v25, v41
	v_fmac_f32_e32 v81, v30, v41
	v_fmac_f32_e32 v80, v26, v41
	v_fmac_f32_e32 v79, v13, v41
	v_fmac_f32_e32 v78, v11, v41
	v_fmac_f32_e32 v77, v12, v41
	v_fmac_f32_e32 v70, v14, v41
	v_fmac_f32_e32 v69, v15, v41
	v_fmac_f32_e32 v64, v31, v41
	v_fmac_f32_e32 v62, v32, v41
	v_fmac_f32_e32 v55, v16, v41
	v_fmac_f32_e32 v54, v33, v41
	v_fmac_f32_e32 v52, v17, v41
	v_fmac_f32_e32 v51, v18, v41
	v_fmac_f32_e32 v50, v4, v41
	v_fmac_f32_e32 v49, v6, v41
	v_fmac_f32_e32 v46, v0, v41
	v_fmac_f32_e32 v45, v5, v41
	v_fmac_f32_e32 v44, v7, v41
	v_fmac_f32_e32 v43, v8, v41
	v_fmac_f32_e32 v40, v9, v41
	v_fma_f32 v41, v10, v41, v34
	v_fmac_f32_e32 v93, v20, v38
	v_fmac_f32_e32 v90, v22, v38
	v_fmac_f32_e32 v2, v19, v38
	v_fmac_f32_e32 v86, v21, v38
	v_fmac_f32_e32 v3, v23, v38
	v_fmac_f32_e32 v84, v24, v38
	v_fmac_f32_e32 v83, v28, v38
	v_fmac_f32_e32 v82, v29, v38
	v_fmac_f32_e32 v81, v25, v38
	v_fmac_f32_e32 v80, v30, v38
	v_fmac_f32_e32 v79, v26, v38
	v_fmac_f32_e32 v78, v13, v38
	v_fmac_f32_e32 v77, v11, v38
	v_fmac_f32_e32 v70, v12, v38
	v_fmac_f32_e32 v69, v14, v38
	v_fmac_f32_e32 v64, v15, v38
	v_fmac_f32_e32 v62, v31, v38
	v_fmac_f32_e32 v55, v32, v38
	v_fmac_f32_e32 v54, v16, v38
	v_fmac_f32_e32 v52, v33, v38
	v_fmac_f32_e32 v51, v17, v38
	v_fmac_f32_e32 v50, v18, v38
	v_fmac_f32_e32 v49, v4, v38
	v_fmac_f32_e32 v46, v6, v38
	v_fmac_f32_e32 v45, v0, v38
	v_fmac_f32_e32 v44, v5, v38
	v_fmac_f32_e32 v43, v7, v38
	v_fmac_f32_e32 v40, v8, v38
	v_fmac_f32_e32 v41, v9, v38
	v_fma_f32 v38, v10, v38, v34
	v_fmac_f32_e32 v93, v27, v37
	v_fmac_f32_e32 v90, v20, v37
	v_fmac_f32_e32 v2, v22, v37
	v_fmac_f32_e32 v86, v19, v37
	v_fmac_f32_e32 v3, v21, v37
	v_fmac_f32_e32 v84, v23, v37
	v_fmac_f32_e32 v83, v24, v37
	v_fmac_f32_e32 v82, v28, v37
	v_fmac_f32_e32 v81, v29, v37
	v_fmac_f32_e32 v80, v25, v37
	v_fmac_f32_e32 v79, v30, v37
	v_fmac_f32_e32 v78, v26, v37
	v_fmac_f32_e32 v77, v13, v37
	v_fmac_f32_e32 v70, v11, v37
	v_fmac_f32_e32 v69, v12, v37
	v_fmac_f32_e32 v64, v14, v37
	v_fmac_f32_e32 v62, v15, v37
	v_fmac_f32_e32 v55, v31, v37
	v_fmac_f32_e32 v54, v32, v37
	v_fmac_f32_e32 v52, v16, v37
	v_fmac_f32_e32 v51, v33, v37
	v_fmac_f32_e32 v50, v17, v37
	v_fmac_f32_e32 v49, v18, v37
	v_fmac_f32_e32 v46, v4, v37
	v_fmac_f32_e32 v45, v6, v37
	v_fmac_f32_e32 v44, v0, v37
	v_fmac_f32_e32 v43, v5, v37
	v_fmac_f32_e32 v40, v7, v37
	v_fmac_f32_e32 v41, v8, v37
	v_fmac_f32_e32 v38, v9, v37
	v_fma_f32 v37, v10, v37, v34
	v_fmac_f32_e32 v34, v10, v36
	v_fmac_f32_e32 v37, v9, v36
	v_fmac_f32_e32 v34, v9, v39
	v_fmac_f32_e32 v38, v8, v36
	v_fmac_f32_e32 v37, v8, v39
	v_fmac_f32_e32 v34, v8, v42
	v_fmac_f32_e32 v41, v7, v36
	v_fmac_f32_e32 v38, v7, v39
	v_fmac_f32_e32 v37, v7, v42
	v_fmac_f32_e32 v34, v7, v47
	v_fmac_f32_e32 v40, v5, v36
	v_fmac_f32_e32 v41, v5, v39
	v_fmac_f32_e32 v38, v5, v42
	v_fmac_f32_e32 v37, v5, v47
	v_fmac_f32_e32 v34, v5, v48
	v_fmac_f32_e32 v43, v0, v36
	v_fmac_f32_e32 v40, v0, v39
	v_fmac_f32_e32 v41, v0, v42
	v_fmac_f32_e32 v38, v0, v47
	v_fmac_f32_e32 v37, v0, v48
	v_fmac_f32_e32 v34, v0, v53
	v_fmac_f32_e32 v44, v6, v36
	v_fmac_f32_e32 v43, v6, v39
	v_fmac_f32_e32 v40, v6, v42
	v_fmac_f32_e32 v41, v6, v47
	v_fmac_f32_e32 v38, v6, v48
	v_fmac_f32_e32 v37, v6, v53
	v_fmac_f32_e32 v34, v6, v56
	v_fmac_f32_e32 v45, v4, v36
	v_fmac_f32_e32 v44, v4, v39
	v_fmac_f32_e32 v43, v4, v42
	v_fmac_f32_e32 v40, v4, v47
	v_fmac_f32_e32 v41, v4, v48
	v_fmac_f32_e32 v38, v4, v53
	v_fmac_f32_e32 v37, v4, v56
	v_fmac_f32_e32 v34, v4, v57
	v_fmac_f32_e32 v46, v18, v36
	v_fmac_f32_e32 v45, v18, v39
	v_fmac_f32_e32 v44, v18, v42
	v_fmac_f32_e32 v43, v18, v47
	v_fmac_f32_e32 v40, v18, v48
	v_fmac_f32_e32 v41, v18, v53
	v_fmac_f32_e32 v38, v18, v56
	v_fmac_f32_e32 v37, v18, v57
	v_fmac_f32_e32 v34, v18, v58
	v_fmac_f32_e32 v49, v17, v36
	v_fmac_f32_e32 v46, v17, v39
	v_fmac_f32_e32 v45, v17, v42
	v_fmac_f32_e32 v44, v17, v47
	v_fmac_f32_e32 v43, v17, v48
	v_fmac_f32_e32 v40, v17, v53
	v_fmac_f32_e32 v41, v17, v56
	v_fmac_f32_e32 v38, v17, v57
	v_fmac_f32_e32 v37, v17, v58
	v_fmac_f32_e32 v34, v17, v59
; __device__ __forceinline__ void conv_item(LAS unsigned char* lds, const bf16* PROJ, bf16* MIX, const float* cw, const float* cb, const float* lg, const float* lb, int item, int tid) {
;     ...
;     for (int tk = 0; tk < 32; ++tk) { float s = bias;
; #pragma unroll
;         for (int k = 0; k < 31; ++k) s += w[k] * hw[tk + k];
;         acc[tk] = s; }
	v_fmac_f32_e32 v50, v33, v36
	v_fmac_f32_e32 v49, v33, v39
	v_fmac_f32_e32 v46, v33, v42
	v_fmac_f32_e32 v45, v33, v47
	v_fmac_f32_e32 v44, v33, v48
	v_fmac_f32_e32 v43, v33, v53
	v_fmac_f32_e32 v40, v33, v56
	v_fmac_f32_e32 v41, v33, v57
	v_fmac_f32_e32 v38, v33, v58
	v_fmac_f32_e32 v37, v33, v59
	v_fmac_f32_e32 v34, v33, v60
	v_fmac_f32_e32 v51, v16, v36
	v_fmac_f32_e32 v50, v16, v39
	v_fmac_f32_e32 v49, v16, v42
	v_fmac_f32_e32 v46, v16, v47
	v_fmac_f32_e32 v45, v16, v48
	v_fmac_f32_e32 v44, v16, v53
	v_fmac_f32_e32 v43, v16, v56
	v_fmac_f32_e32 v40, v16, v57
	v_fmac_f32_e32 v41, v16, v58
	v_fmac_f32_e32 v38, v16, v59
	v_fmac_f32_e32 v37, v16, v60
	v_fmac_f32_e32 v34, v16, v61
	v_fmac_f32_e32 v52, v32, v36
	v_fmac_f32_e32 v51, v32, v39
	v_fmac_f32_e32 v50, v32, v42
	v_fmac_f32_e32 v49, v32, v47
	v_fmac_f32_e32 v46, v32, v48
	v_fmac_f32_e32 v45, v32, v53
	v_fmac_f32_e32 v44, v32, v56
	v_fmac_f32_e32 v43, v32, v57
	v_fmac_f32_e32 v40, v32, v58
	v_fmac_f32_e32 v41, v32, v59
	v_fmac_f32_e32 v38, v32, v60
	v_fmac_f32_e32 v37, v32, v61
	v_fmac_f32_e32 v34, v32, v63
	v_fmac_f32_e32 v54, v31, v36
	v_fmac_f32_e32 v52, v31, v39
	v_fmac_f32_e32 v51, v31, v42
	v_fmac_f32_e32 v50, v31, v47
	v_fmac_f32_e32 v49, v31, v48
	v_fmac_f32_e32 v46, v31, v53
	v_fmac_f32_e32 v45, v31, v56
	v_fmac_f32_e32 v44, v31, v57
	v_fmac_f32_e32 v43, v31, v58
	v_fmac_f32_e32 v40, v31, v59
	v_fmac_f32_e32 v41, v31, v60
	v_fmac_f32_e32 v38, v31, v61
	v_fmac_f32_e32 v37, v31, v63
	v_fmac_f32_e32 v34, v31, v65
	v_fmac_f32_e32 v55, v15, v36
	v_fmac_f32_e32 v54, v15, v39
	v_fmac_f32_e32 v52, v15, v42
	v_fmac_f32_e32 v51, v15, v47
	v_fmac_f32_e32 v50, v15, v48
	v_fmac_f32_e32 v49, v15, v53
	v_fmac_f32_e32 v46, v15, v56
	v_fmac_f32_e32 v45, v15, v57
	v_fmac_f32_e32 v44, v15, v58
	v_fmac_f32_e32 v43, v15, v59
	v_fmac_f32_e32 v40, v15, v60
	v_fmac_f32_e32 v41, v15, v61
	v_fmac_f32_e32 v38, v15, v63
	v_fmac_f32_e32 v37, v15, v65
	v_fmac_f32_e32 v34, v15, v66
	v_fmac_f32_e32 v62, v14, v36
	v_fmac_f32_e32 v55, v14, v39
	v_fmac_f32_e32 v54, v14, v42
	v_fmac_f32_e32 v52, v14, v47
	v_fmac_f32_e32 v51, v14, v48
	v_fmac_f32_e32 v50, v14, v53
	v_fmac_f32_e32 v49, v14, v56
	v_fmac_f32_e32 v46, v14, v57
	v_fmac_f32_e32 v45, v14, v58
	v_fmac_f32_e32 v44, v14, v59
	v_fmac_f32_e32 v43, v14, v60
	v_fmac_f32_e32 v40, v14, v61
	v_fmac_f32_e32 v41, v14, v63
	v_fmac_f32_e32 v38, v14, v65
	v_fmac_f32_e32 v37, v14, v66
	v_fmac_f32_e32 v34, v14, v67
	v_fmac_f32_e32 v64, v12, v36
	v_fmac_f32_e32 v62, v12, v39
	v_fmac_f32_e32 v55, v12, v42
	v_fmac_f32_e32 v54, v12, v47
	v_fmac_f32_e32 v52, v12, v48
	v_fmac_f32_e32 v51, v12, v53
	v_fmac_f32_e32 v50, v12, v56
	v_fmac_f32_e32 v49, v12, v57
	v_fmac_f32_e32 v46, v12, v58
	v_fmac_f32_e32 v45, v12, v59
	v_fmac_f32_e32 v44, v12, v60
	v_fmac_f32_e32 v43, v12, v61
	v_fmac_f32_e32 v40, v12, v63
	v_fmac_f32_e32 v41, v12, v65
	v_fmac_f32_e32 v38, v12, v66
	v_fmac_f32_e32 v37, v12, v67
	v_fmac_f32_e32 v34, v12, v68
	v_fmac_f32_e32 v69, v11, v36
	v_fmac_f32_e32 v64, v11, v39
	v_fmac_f32_e32 v62, v11, v42
	v_fmac_f32_e32 v55, v11, v47
	v_fmac_f32_e32 v54, v11, v48
	v_fmac_f32_e32 v52, v11, v53
	v_fmac_f32_e32 v51, v11, v56
	v_fmac_f32_e32 v50, v11, v57
	v_fmac_f32_e32 v49, v11, v58
	v_fmac_f32_e32 v46, v11, v59
	v_fmac_f32_e32 v45, v11, v60
	v_fmac_f32_e32 v44, v11, v61
	v_fmac_f32_e32 v43, v11, v63
	v_fmac_f32_e32 v40, v11, v65
	v_fmac_f32_e32 v41, v11, v66
	v_fmac_f32_e32 v38, v11, v67
	v_fmac_f32_e32 v37, v11, v68
	v_fmac_f32_e32 v34, v11, v71
	v_fmac_f32_e32 v70, v13, v36
	v_fmac_f32_e32 v69, v13, v39
	v_fmac_f32_e32 v64, v13, v42
	v_fmac_f32_e32 v62, v13, v47
	v_fmac_f32_e32 v55, v13, v48
	v_fmac_f32_e32 v54, v13, v53
	v_fmac_f32_e32 v52, v13, v56
	v_fmac_f32_e32 v51, v13, v57
	v_fmac_f32_e32 v50, v13, v58
	v_fmac_f32_e32 v49, v13, v59
	v_fmac_f32_e32 v46, v13, v60
	v_fmac_f32_e32 v45, v13, v61
	v_fmac_f32_e32 v44, v13, v63
	v_fmac_f32_e32 v43, v13, v65
	v_fmac_f32_e32 v40, v13, v66
	v_fmac_f32_e32 v41, v13, v67
	v_fmac_f32_e32 v38, v13, v68
	v_fmac_f32_e32 v37, v13, v71
	v_fmac_f32_e32 v34, v13, v72
	v_fmac_f32_e32 v77, v26, v36
	v_fmac_f32_e32 v70, v26, v39
	v_fmac_f32_e32 v69, v26, v42
	v_fmac_f32_e32 v64, v26, v47
	v_fmac_f32_e32 v62, v26, v48
	v_fmac_f32_e32 v55, v26, v53
	v_fmac_f32_e32 v54, v26, v56
	v_fmac_f32_e32 v52, v26, v57
	v_fmac_f32_e32 v51, v26, v58
	v_fmac_f32_e32 v50, v26, v59
	v_fmac_f32_e32 v49, v26, v60
	v_fmac_f32_e32 v46, v26, v61
	v_fmac_f32_e32 v45, v26, v63
	v_fmac_f32_e32 v44, v26, v65
	v_fmac_f32_e32 v43, v26, v66
	v_fmac_f32_e32 v40, v26, v67
	v_fmac_f32_e32 v41, v26, v68
	v_fmac_f32_e32 v38, v26, v71
	v_fmac_f32_e32 v37, v26, v72
	v_fmac_f32_e32 v34, v26, v73
	v_fmac_f32_e32 v78, v30, v36
	v_fmac_f32_e32 v77, v30, v39
	v_fmac_f32_e32 v70, v30, v42
	v_fmac_f32_e32 v69, v30, v47
	v_fmac_f32_e32 v64, v30, v48
	v_fmac_f32_e32 v62, v30, v53
	v_fmac_f32_e32 v55, v30, v56
	v_fmac_f32_e32 v54, v30, v57
	v_fmac_f32_e32 v52, v30, v58
	v_fmac_f32_e32 v51, v30, v59
	v_fmac_f32_e32 v50, v30, v60
	v_fmac_f32_e32 v49, v30, v61
	v_fmac_f32_e32 v46, v30, v63
	v_fmac_f32_e32 v45, v30, v65
	v_fmac_f32_e32 v44, v30, v66
	v_fmac_f32_e32 v43, v30, v67
	v_fmac_f32_e32 v40, v30, v68
	v_fmac_f32_e32 v41, v30, v71
	v_fmac_f32_e32 v38, v30, v72
	v_fmac_f32_e32 v37, v30, v73
	v_fmac_f32_e32 v34, v30, v74
	v_fmac_f32_e32 v79, v25, v36
	v_fmac_f32_e32 v78, v25, v39
	v_fmac_f32_e32 v77, v25, v42
	v_fmac_f32_e32 v70, v25, v47
	v_fmac_f32_e32 v69, v25, v48
	v_fmac_f32_e32 v64, v25, v53
	v_fmac_f32_e32 v62, v25, v56
	v_fmac_f32_e32 v55, v25, v57
	v_fmac_f32_e32 v54, v25, v58
	v_fmac_f32_e32 v52, v25, v59
	v_fmac_f32_e32 v51, v25, v60
	v_fmac_f32_e32 v50, v25, v61
; __device__ __forceinline__ void conv_item(LAS unsigned char* lds, const bf16* PROJ, bf16* MIX, const float* cw, const float* cb, const float* lg, const float* lb, int item, int tid) {
;     ...
;     for (int tk = 0; tk < 32; ++tk) { float s = bias;
; #pragma unroll
;         for (int k = 0; k < 31; ++k) s += w[k] * hw[tk + k];
;         acc[tk] = s; }
	v_fmac_f32_e32 v49, v25, v63
	v_fmac_f32_e32 v46, v25, v65
	v_fmac_f32_e32 v45, v25, v66
	v_fmac_f32_e32 v44, v25, v67
	v_fmac_f32_e32 v43, v25, v68
	v_fmac_f32_e32 v40, v25, v71
	v_fmac_f32_e32 v41, v25, v72
	v_fmac_f32_e32 v38, v25, v73
	v_fmac_f32_e32 v37, v25, v74
	v_fmac_f32_e32 v34, v25, v75
	v_fmac_f32_e32 v80, v29, v36
	v_fmac_f32_e32 v79, v29, v39
	v_fmac_f32_e32 v78, v29, v42
	v_fmac_f32_e32 v77, v29, v47
	v_fmac_f32_e32 v70, v29, v48
	v_fmac_f32_e32 v69, v29, v53
	v_fmac_f32_e32 v64, v29, v56
	v_fmac_f32_e32 v62, v29, v57
	v_fmac_f32_e32 v55, v29, v58
	v_fmac_f32_e32 v54, v29, v59
	v_fmac_f32_e32 v52, v29, v60
	v_fmac_f32_e32 v51, v29, v61
	v_fmac_f32_e32 v50, v29, v63
	v_fmac_f32_e32 v49, v29, v65
	v_fmac_f32_e32 v46, v29, v66
	v_fmac_f32_e32 v45, v29, v67
	v_fmac_f32_e32 v44, v29, v68
	v_fmac_f32_e32 v43, v29, v71
	v_fmac_f32_e32 v40, v29, v72
	v_fmac_f32_e32 v41, v29, v73
	v_fmac_f32_e32 v38, v29, v74
	v_fmac_f32_e32 v37, v29, v75
	v_fmac_f32_e32 v34, v29, v76
	v_fmac_f32_e32 v81, v28, v36
	v_fmac_f32_e32 v80, v28, v39
	v_fmac_f32_e32 v79, v28, v42
	v_fmac_f32_e32 v78, v28, v47
	v_fmac_f32_e32 v77, v28, v48
	v_fmac_f32_e32 v70, v28, v53
	v_fmac_f32_e32 v69, v28, v56
	v_fmac_f32_e32 v64, v28, v57
	v_fmac_f32_e32 v62, v28, v58
	v_fmac_f32_e32 v55, v28, v59
	v_fmac_f32_e32 v54, v28, v60
	v_fmac_f32_e32 v52, v28, v61
	v_fmac_f32_e32 v51, v28, v63
	v_fmac_f32_e32 v50, v28, v65
	v_fmac_f32_e32 v49, v28, v66
	v_fmac_f32_e32 v46, v28, v67
	v_fmac_f32_e32 v45, v28, v68
	v_fmac_f32_e32 v44, v28, v71
	v_fmac_f32_e32 v43, v28, v72
	v_fmac_f32_e32 v40, v28, v73
	v_fmac_f32_e32 v41, v28, v74
	v_fmac_f32_e32 v38, v28, v75
	v_fmac_f32_e32 v37, v28, v76
	v_fmac_f32_e32 v34, v28, v87
	v_fmac_f32_e32 v82, v24, v36
	v_fmac_f32_e32 v81, v24, v39
	v_fmac_f32_e32 v80, v24, v42
	v_fmac_f32_e32 v79, v24, v47
	v_fmac_f32_e32 v78, v24, v48
	v_fmac_f32_e32 v77, v24, v53
	v_fmac_f32_e32 v70, v24, v56
	v_fmac_f32_e32 v69, v24, v57
	v_fmac_f32_e32 v64, v24, v58
	v_fmac_f32_e32 v62, v24, v59
	v_fmac_f32_e32 v55, v24, v60
	v_fmac_f32_e32 v54, v24, v61
	v_fmac_f32_e32 v52, v24, v63
	v_fmac_f32_e32 v51, v24, v65
	v_fmac_f32_e32 v50, v24, v66
	v_fmac_f32_e32 v49, v24, v67
	v_fmac_f32_e32 v46, v24, v68
	v_fmac_f32_e32 v45, v24, v71
	v_fmac_f32_e32 v44, v24, v72
	v_fmac_f32_e32 v43, v24, v73
	v_fmac_f32_e32 v40, v24, v74
	v_fmac_f32_e32 v41, v24, v75
	v_fmac_f32_e32 v38, v24, v76
	v_fmac_f32_e32 v37, v24, v87
	v_fmac_f32_e32 v34, v24, v88
	v_fmac_f32_e32 v83, v23, v36
	v_fmac_f32_e32 v82, v23, v39
	v_fmac_f32_e32 v81, v23, v42
	v_fmac_f32_e32 v80, v23, v47
	v_fmac_f32_e32 v79, v23, v48
	v_fmac_f32_e32 v78, v23, v53
	v_fmac_f32_e32 v77, v23, v56
	v_fmac_f32_e32 v70, v23, v57
	v_fmac_f32_e32 v69, v23, v58
	v_fmac_f32_e32 v64, v23, v59
	v_fmac_f32_e32 v62, v23, v60
	v_fmac_f32_e32 v55, v23, v61
	v_fmac_f32_e32 v54, v23, v63
	v_fmac_f32_e32 v52, v23, v65
	v_fmac_f32_e32 v51, v23, v66
	v_fmac_f32_e32 v50, v23, v67
	v_fmac_f32_e32 v49, v23, v68
	v_fmac_f32_e32 v46, v23, v71
	v_fmac_f32_e32 v45, v23, v72
	v_fmac_f32_e32 v44, v23, v73
	v_fmac_f32_e32 v43, v23, v74
	v_fmac_f32_e32 v40, v23, v75
	v_fmac_f32_e32 v41, v23, v76
	v_fmac_f32_e32 v38, v23, v87
	v_fmac_f32_e32 v37, v23, v88
	v_fmac_f32_e32 v34, v23, v89
	v_fmac_f32_e32 v84, v21, v36
	v_fmac_f32_e32 v83, v21, v39
	v_fmac_f32_e32 v82, v21, v42
	v_fmac_f32_e32 v81, v21, v47
	v_fmac_f32_e32 v80, v21, v48
	v_fmac_f32_e32 v79, v21, v53
	v_fmac_f32_e32 v78, v21, v56
	v_fmac_f32_e32 v77, v21, v57
	v_fmac_f32_e32 v70, v21, v58
	v_fmac_f32_e32 v69, v21, v59
	v_fmac_f32_e32 v64, v21, v60
	v_fmac_f32_e32 v62, v21, v61
	v_fmac_f32_e32 v55, v21, v63
	v_fmac_f32_e32 v54, v21, v65
	v_fmac_f32_e32 v52, v21, v66
	v_fmac_f32_e32 v51, v21, v67
	v_fmac_f32_e32 v50, v21, v68
	v_fmac_f32_e32 v49, v21, v71
	v_fmac_f32_e32 v46, v21, v72
	v_fmac_f32_e32 v45, v21, v73
	v_fmac_f32_e32 v44, v21, v74
	v_fmac_f32_e32 v43, v21, v75
	v_fmac_f32_e32 v40, v21, v76
	v_fmac_f32_e32 v41, v21, v87
	v_fmac_f32_e32 v38, v21, v88
	v_fmac_f32_e32 v37, v21, v89
	v_fmac_f32_e32 v34, v21, v92
	v_fmac_f32_e32 v3, v19, v36
	v_fmac_f32_e32 v84, v19, v39
	v_fmac_f32_e32 v83, v19, v42
	v_fmac_f32_e32 v82, v19, v47
	v_fmac_f32_e32 v81, v19, v48
	v_fmac_f32_e32 v80, v19, v53
	v_fmac_f32_e32 v79, v19, v56
	v_fmac_f32_e32 v78, v19, v57
	v_fmac_f32_e32 v77, v19, v58
	v_fmac_f32_e32 v70, v19, v59
	v_fmac_f32_e32 v69, v19, v60
	v_fmac_f32_e32 v64, v19, v61
	v_fmac_f32_e32 v62, v19, v63
	v_fmac_f32_e32 v55, v19, v65
	v_fmac_f32_e32 v54, v19, v66
	v_fmac_f32_e32 v52, v19, v67
	v_fmac_f32_e32 v51, v19, v68
	v_fmac_f32_e32 v50, v19, v71
	v_fmac_f32_e32 v49, v19, v72
	v_fmac_f32_e32 v46, v19, v73
	v_fmac_f32_e32 v45, v19, v74
	v_fmac_f32_e32 v44, v19, v75
	v_fmac_f32_e32 v43, v19, v76
	v_fmac_f32_e32 v40, v19, v87
	v_fmac_f32_e32 v41, v19, v88
	v_fmac_f32_e32 v38, v19, v89
	v_fmac_f32_e32 v37, v19, v92
	v_fmac_f32_e32 v34, v19, v94
	v_fmac_f32_e32 v86, v22, v36
	v_fmac_f32_e32 v3, v22, v39
	v_fmac_f32_e32 v84, v22, v42
	v_fmac_f32_e32 v83, v22, v47
	v_fmac_f32_e32 v82, v22, v48
	v_fmac_f32_e32 v81, v22, v53
	v_fmac_f32_e32 v80, v22, v56
	v_fmac_f32_e32 v79, v22, v57
	v_fmac_f32_e32 v78, v22, v58
	v_fmac_f32_e32 v77, v22, v59
	v_fmac_f32_e32 v70, v22, v60
	v_fmac_f32_e32 v69, v22, v61
	v_fmac_f32_e32 v64, v22, v63
	v_fmac_f32_e32 v62, v22, v65
	v_fmac_f32_e32 v55, v22, v66
	v_fmac_f32_e32 v54, v22, v67
	v_fmac_f32_e32 v52, v22, v68
	v_fmac_f32_e32 v51, v22, v71
	v_fmac_f32_e32 v50, v22, v72
	v_fmac_f32_e32 v49, v22, v73
	v_fmac_f32_e32 v46, v22, v74
	v_fmac_f32_e32 v45, v22, v75
	v_fmac_f32_e32 v44, v22, v76
	v_fmac_f32_e32 v43, v22, v87
	v_fmac_f32_e32 v40, v22, v88
; #define LAS __attribute__((address_space(3)))
; __device__ __forceinline__ void conv_item(LAS unsigned char* lds, const bf16* PROJ, bf16* MIX, const float* cw, const float* cb, const float* lg, const float* lb, int item, int tid) {
;     ...
;     LAS float* cbuf = (LAS float*)lds; LAS float* st = (LAS float*)(lds + 32 * 512 * 4);
; #pragma unroll
;     for (int tk = 0; tk < 32; ++tk) cbuf[tk * 512 + c] = acc[tk];
;     __syncthreads();
; #pragma unroll
;     for (int q = 0; q < 4; ++q) { const int tk = 4 * wid + q; float v[8]; float s = 0.f;
; #pragma unroll
;         for (int i = 0; i < 8; ++i) { v[i] = cbuf[tk * 512 + lane + 64 * i]; s += v[i]; }
;         const float mean = wave_sum(s, lane) * (1.f / 512.f); float s2 = 0.f;
; #pragma unroll
;         for (int i = 0; i < 8; ++i) { const float d = v[i] - mean; s2 += d * d; }
;         const float rstd = 1.0f / sqrtf(wave_sum(s2, lane) * (1.f / 512.f) + 1e-5f);
;         if (lane == 0) { st[2 * tk] = mean; st[2 * tk + 1] = rstd; } }
	v_fmac_f32_e32 v41, v22, v89
	v_fmac_f32_e32 v38, v22, v92
	v_fmac_f32_e32 v37, v22, v94
	v_fmac_f32_e32 v34, v22, v95
	v_fmac_f32_e32 v90, v27, v36
	v_fmac_f32_e32 v2, v20, v36
	v_fmac_f32_e32 v86, v20, v39
	v_fmac_f32_e32 v3, v20, v42
	v_fmac_f32_e32 v84, v20, v47
	v_fmac_f32_e32 v83, v20, v48
	v_fmac_f32_e32 v82, v20, v53
	v_fmac_f32_e32 v81, v20, v56
	v_fmac_f32_e32 v80, v20, v57
	v_fmac_f32_e32 v79, v20, v58
	v_fmac_f32_e32 v78, v20, v59
	v_fmac_f32_e32 v77, v20, v60
	v_fmac_f32_e32 v70, v20, v61
	v_fmac_f32_e32 v69, v20, v63
	v_fmac_f32_e32 v64, v20, v65
	v_fmac_f32_e32 v62, v20, v66
	v_fmac_f32_e32 v55, v20, v67
	v_fmac_f32_e32 v54, v20, v68
	v_fmac_f32_e32 v52, v20, v71
	v_fmac_f32_e32 v51, v20, v72
	v_fmac_f32_e32 v50, v20, v73
	v_fmac_f32_e32 v49, v20, v74
	v_fmac_f32_e32 v46, v20, v75
	v_fmac_f32_e32 v45, v20, v76
	v_fmac_f32_e32 v44, v20, v87
	v_fmac_f32_e32 v43, v20, v88
	v_fmac_f32_e32 v40, v20, v89
	v_fmac_f32_e32 v41, v20, v92
	v_fmac_f32_e32 v38, v20, v94
	v_fmac_f32_e32 v37, v20, v95
	v_fmac_f32_e32 v34, v20, v96
	v_lshl_add_u32 v0, v200, 2, 0
	v_fmac_f32_e32 v2, v27, v39
	v_fmac_f32_e32 v86, v27, v42
	v_fmac_f32_e32 v3, v27, v47
	v_fmac_f32_e32 v84, v27, v48
	v_fmac_f32_e32 v83, v27, v53
	v_fmac_f32_e32 v82, v27, v56
	v_fmac_f32_e32 v81, v27, v57
	v_fmac_f32_e32 v80, v27, v58
	v_fmac_f32_e32 v79, v27, v59
	v_fmac_f32_e32 v78, v27, v60
	v_fmac_f32_e32 v77, v27, v61
	v_fmac_f32_e32 v70, v27, v63
	v_fmac_f32_e32 v69, v27, v65
	v_fmac_f32_e32 v64, v27, v66
	v_fmac_f32_e32 v62, v27, v67
	v_fmac_f32_e32 v55, v27, v68
	v_fmac_f32_e32 v54, v27, v71
	v_fmac_f32_e32 v52, v27, v72
	v_fmac_f32_e32 v51, v27, v73
	v_fmac_f32_e32 v50, v27, v74
	v_fmac_f32_e32 v49, v27, v75
	v_fmac_f32_e32 v46, v27, v76
	v_fmac_f32_e32 v45, v27, v87
	v_fmac_f32_e32 v44, v27, v88
	v_fmac_f32_e32 v43, v27, v89
	v_fmac_f32_e32 v40, v27, v92
	v_fmac_f32_e32 v41, v27, v94
	v_fmac_f32_e32 v38, v27, v95
	v_fmac_f32_e32 v37, v27, v96
	v_fmac_f32_e32 v34, v27, v97
	ds_write2st64_b32 v0, v93, v90 offset1:8
	ds_write2st64_b32 v0, v2, v86 offset0:16 offset1:24
	ds_write2st64_b32 v0, v3, v84 offset0:32 offset1:40
	ds_write2st64_b32 v0, v83, v82 offset0:48 offset1:56
	ds_write2st64_b32 v0, v81, v80 offset0:64 offset1:72
	ds_write2st64_b32 v0, v79, v78 offset0:80 offset1:88
	ds_write2st64_b32 v0, v77, v70 offset0:96 offset1:104
	ds_write2st64_b32 v0, v69, v64 offset0:112 offset1:120
	ds_write2st64_b32 v0, v62, v55 offset0:128 offset1:136
	ds_write2st64_b32 v0, v54, v52 offset0:144 offset1:152
	ds_write2st64_b32 v0, v51, v50 offset0:160 offset1:168
	ds_write2st64_b32 v0, v49, v46 offset0:176 offset1:184
	ds_write2st64_b32 v0, v45, v44 offset0:192 offset1:200
	ds_write2st64_b32 v0, v43, v40 offset0:208 offset1:216
	ds_write2st64_b32 v0, v41, v38 offset0:224 offset1:232
	ds_write2st64_b32 v0, v37, v34 offset0:240 offset1:248
	v_lshlrev_b32_e32 v0, 2, v35
	v_add_u32_e32 v9, 0, v0
	v_lshl_add_u32 v10, s4, 11, v9
	s_waitcnt lgkmcnt(0)
	s_barrier
	ds_read2st64_b32 v[12:13], v10 offset1:1
	ds_read2st64_b32 v[14:15], v10 offset0:2 offset1:3
	ds_read2st64_b32 v[16:17], v10 offset0:4 offset1:5
	ds_read2st64_b32 v[18:19], v10 offset0:6 offset1:7
	v_xor_b32_e32 v8, 4, v0
	s_waitcnt lgkmcnt(3)
	v_add_f32_e32 v11, 0, v12
	v_add_f32_e32 v11, v11, v13
	s_waitcnt lgkmcnt(2)
	v_add_f32_e32 v11, v11, v14
	v_add_f32_e32 v11, v11, v15
	s_waitcnt lgkmcnt(1)
	v_add_f32_e32 v11, v11, v16
	v_add_f32_e32 v11, v11, v17
	s_waitcnt lgkmcnt(0)
	v_add_f32_e32 v10, v11, v18
	v_add_f32_e32 v10, v10, v19
	ds_bpermute_b32 v11, v8, v10
	v_xor_b32_e32 v7, 8, v0
	v_xor_b32_e32 v6, 16, v0
	v_xor_b32_e32 v5, 32, v0
	v_xor_b32_e32 v4, 64, v0
	s_waitcnt lgkmcnt(0)
	v_add_f32_e32 v10, v10, v11
	ds_bpermute_b32 v11, v7, v10
	v_xor_b32_e32 v0, 0x80, v0
	s_waitcnt lgkmcnt(0)
	v_add_f32_e32 v10, v10, v11
	ds_bpermute_b32 v11, v6, v10
	s_waitcnt lgkmcnt(0)
	v_add_f32_e32 v10, v10, v11
	ds_bpermute_b32 v11, v5, v10
	s_waitcnt lgkmcnt(0)
	v_add_f32_e32 v10, v10, v11
	ds_bpermute_b32 v11, v4, v10
	s_waitcnt lgkmcnt(0)
	v_add_f32_e32 v10, v10, v11
	ds_bpermute_b32 v11, v0, v10
	s_waitcnt lgkmcnt(0)
	v_add_f32_e32 v10, v10, v11
	v_fmac_f32_e32 v13, 0xbb000000, v10
	v_fmamk_f32 v11, v10, 0xbb000000, v12
	v_mul_f32_e32 v12, v13, v13
	v_fmac_f32_e32 v12, v11, v11
	v_fmamk_f32 v11, v10, 0xbb000000, v14
	v_fmac_f32_e32 v12, v11, v11
	v_fmac_f32_e32 v15, 0xbb000000, v10
	v_fmac_f32_e32 v12, v15, v15
	v_fmamk_f32 v11, v10, 0xbb000000, v16
	v_fmac_f32_e32 v12, v11, v11
	v_fmac_f32_e32 v17, 0xbb000000, v10
	v_fmac_f32_e32 v12, v17, v17
	v_fmamk_f32 v11, v10, 0xbb000000, v18
	v_fmac_f32_e32 v12, v11, v11
	v_fmac_f32_e32 v19, 0xbb000000, v10
	v_fmac_f32_e32 v12, v19, v19
	ds_bpermute_b32 v11, v8, v12
	s_waitcnt lgkmcnt(0)
	v_add_f32_e32 v11, v12, v11
	ds_bpermute_b32 v12, v7, v11
	s_waitcnt lgkmcnt(0)
	v_add_f32_e32 v11, v11, v12
	ds_bpermute_b32 v12, v6, v11
	s_waitcnt lgkmcnt(0)
	v_add_f32_e32 v11, v11, v12
	ds_bpermute_b32 v12, v5, v11
	s_waitcnt lgkmcnt(0)
	v_add_f32_e32 v11, v11, v12
	ds_bpermute_b32 v12, v4, v11
	s_waitcnt lgkmcnt(0)
	v_add_f32_e32 v11, v11, v12
	ds_bpermute_b32 v12, v0, v11
	s_and_saveexec_b64 s[0:1], s[8:9]
	s_cbranch_execz .LBB0_434
	s_waitcnt lgkmcnt(0)
	v_add_f32_e32 v11, v11, v12
	v_fmamk_f32 v11, v11, 0x3b000000, v232
	v_mul_f32_e32 v12, 0x4f800000, v11
	v_cmp_gt_f32_e32 vcc, s80, v11
	s_lshl_b32 s5, s4, 3
	s_add_i32 s5, s5, 0
	v_cndmask_b32_e32 v11, v11, v12, vcc
	v_sqrt_f32_e32 v12, v11
	s_add_i32 s5, s5, 0x10000
	v_mul_f32_e32 v10, 0x3b000000, v10
	v_add_u32_e32 v13, -1, v12
	v_fma_f32 v15, -v13, v12, v11
	v_add_u32_e32 v14, 1, v12
	v_cmp_ge_f32_e64 s[10:11], 0, v15
	s_nop 1
	v_cndmask_b32_e64 v13, v12, v13, s[10:11]
	v_fma_f32 v12, -v14, v12, v11
	v_cmp_lt_f32_e64 s[10:11], 0, v12
	s_nop 1
	v_cndmask_b32_e64 v12, v13, v14, s[10:11]
	v_mul_f32_e32 v13, 0x37800000, v12
	v_cndmask_b32_e32 v12, v12, v13, vcc
	v_cmp_class_f32_e32 vcc, v11, v231
	s_nop 1
	v_cndmask_b32_e32 v11, v12, v11, vcc
	v_div_scale_f32 v12, s[6:7], v11, v11, 1.0
	v_rcp_f32_e32 v13, v12
	s_nop 0
	v_fma_f32 v14, -v12, v13, 1.0
	v_fmac_f32_e32 v13, v14, v13
	v_div_scale_f32 v14, vcc, 1.0, v11, 1.0
	v_mul_f32_e32 v15, v14, v13
	v_fma_f32 v16, -v12, v15, v14
	v_fmac_f32_e32 v15, v16, v13
	v_fma_f32 v12, -v12, v15, v14
	v_div_fmas_f32 v12, v12, v13, v15
	v_div_fixup_f32 v11, v12, v11, 1.0
	v_mov_b32_e32 v12, s5
	ds_write_b64 v12, v[10:11]
